# hand-written final RMSNorm phase (two rows in flight per wave, sample rows compute their own sum of squares); res_fix phase 20 and its grid barrier removed
# speedup vs baseline: 1.1609x; 1.0035x over previous
; template <int EPI> ...
;     ...
;     if (EPI == EPI_SCALE || EPI == EPI_PLAIN || EPI == EPI_FF1) {
; #pragma unroll
;       for (int i = 0; i < 16; i++) {
;         const int rl = rbase + (i & 3) + 8 * (i >> 2);
;         const int row = m0 + rl;
;         float v0 = acc0[i], v1 = acc1[i];
;         if (EPI != EPI_PLAIN) { float rs = sRs[rl]; v0 *= rs; v1 *= rs; }
;         if (EPI == EPI_FF1) { v0 = fmaxf(v0, 0.f); v1 = fmaxf(v1, 0.f); v0 *= v0; v1 *= v1; }
;         outb[(size_t)row * ldo + c0] = f2bf(v0);
;         outb[(size_t)row * ldo + c1] = f2bf(v1);
;       }
.Lgc_tailT:
	v_mfma_f32_16x16x32_bf16 v[0:3], v[194:197], v[178:181], v[0:3]
	v_mfma_f32_16x16x32_bf16 v[4:7], v[198:201], v[178:181], v[4:7]
	v_mfma_f32_16x16x32_bf16 v[8:11], v[202:205], v[178:181], v[8:11]
	v_mfma_f32_16x16x32_bf16 v[12:15], v[206:209], v[178:181], v[12:15]
	v_mfma_f32_16x16x32_bf16 v[16:19], v[210:213], v[178:181], v[16:19]
	v_mfma_f32_16x16x32_bf16 v[20:23], v[214:217], v[178:181], v[20:23]
	v_mfma_f32_16x16x32_bf16 v[24:27], v[218:221], v[178:181], v[24:27]
	v_mfma_f32_16x16x32_bf16 v[28:31], v[222:225], v[178:181], v[28:31]
	v_mfma_f32_16x16x32_bf16 v[32:35], v[194:197], v[182:185], v[32:35]
	v_mfma_f32_16x16x32_bf16 v[36:39], v[198:201], v[182:185], v[36:39]
	v_mfma_f32_16x16x32_bf16 v[40:43], v[202:205], v[182:185], v[40:43]
	v_mfma_f32_16x16x32_bf16 v[44:47], v[206:209], v[182:185], v[44:47]
	v_mfma_f32_16x16x32_bf16 v[48:51], v[210:213], v[182:185], v[48:51]
	v_mfma_f32_16x16x32_bf16 v[52:55], v[214:217], v[182:185], v[52:55]
	v_mfma_f32_16x16x32_bf16 v[56:59], v[218:221], v[182:185], v[56:59]
	v_mfma_f32_16x16x32_bf16 v[60:63], v[222:225], v[182:185], v[60:63]
	v_mfma_f32_16x16x32_bf16 v[64:67], v[194:197], v[186:189], v[64:67]
	v_mfma_f32_16x16x32_bf16 v[68:71], v[198:201], v[186:189], v[68:71]
	v_mfma_f32_16x16x32_bf16 v[72:75], v[202:205], v[186:189], v[72:75]
	v_mfma_f32_16x16x32_bf16 v[76:79], v[206:209], v[186:189], v[76:79]
	v_mfma_f32_16x16x32_bf16 v[80:83], v[210:213], v[186:189], v[80:83]
	v_mfma_f32_16x16x32_bf16 v[84:87], v[214:217], v[186:189], v[84:87]
	v_mfma_f32_16x16x32_bf16 v[88:91], v[218:221], v[186:189], v[88:91]
	v_mfma_f32_16x16x32_bf16 v[92:95], v[222:225], v[186:189], v[92:95]
	v_mfma_f32_16x16x32_bf16 v[96:99], v[194:197], v[190:193], v[96:99]
	v_mfma_f32_16x16x32_bf16 v[100:103], v[198:201], v[190:193], v[100:103]
	v_mfma_f32_16x16x32_bf16 v[104:107], v[202:205], v[190:193], v[104:107]
	v_mfma_f32_16x16x32_bf16 v[108:111], v[206:209], v[190:193], v[108:111]
	v_mfma_f32_16x16x32_bf16 v[112:115], v[210:213], v[190:193], v[112:115]
	v_mfma_f32_16x16x32_bf16 v[116:119], v[214:217], v[190:193], v[116:119]
	v_mfma_f32_16x16x32_bf16 v[120:123], v[218:221], v[190:193], v[120:123]
	v_mfma_f32_16x16x32_bf16 v[124:127], v[222:225], v[190:193], v[124:127]
	s_cmp_eq_u32 s30, 3
	s_cbranch_scc1 .Lgc_epi_res
	s_lshl_b32 s11, s6, 8
	s_lshl_b32 s12, s4, 6
	s_add_u32 s11, s11, s12
	v_add_u32_e32 v238, s11, v248
	v_mul_lo_u32 v230, v238, s24
	s_lshl_b32 s11, s7, 7
	v_and_b32_e32 v239, 1, v249
	v_lshrrev_b32_e32 v240, 1, v249
	v_lshlrev_b32_e32 v239, 4, v239
	v_lshl_add_u32 v239, v240, 3, v239
	v_add_u32_e32 v239, s11, v239
	v_lshlrev_b32_e32 v239, 1, v239
	v_add_u32_e32 v230, v230, v239
	s_lshl_b32 s11, s24, 4
	v_add_u32_e32 v231, s11, v230
	v_add_u32_e32 v232, s11, v231
	v_add_u32_e32 v233, s11, v232
	s_nop 7
	s_cmp_eq_u32 s30, 4
	s_cbranch_scc1 .Lgm_norelu
	v_add_u32_e32 v239, s33, v242
	ds_read_b32 v234, v239
	ds_read_b32 v235, v239 offset:64
	ds_read_b32 v236, v239 offset:128
	ds_read_b32 v237, v239 offset:192
	s_waitcnt lgkmcnt(0)
	v_mul_f32_e32 v0, v0, v234
	v_mul_f32_e32 v1, v1, v234
	v_mul_f32_e32 v2, v2, v234
	v_mul_f32_e32 v3, v3, v234
	v_mul_f32_e32 v4, v4, v234
	v_mul_f32_e32 v5, v5, v234
	v_mul_f32_e32 v6, v6, v234
	v_mul_f32_e32 v7, v7, v234
	v_mul_f32_e32 v8, v8, v234
	v_mul_f32_e32 v9, v9, v234
	v_mul_f32_e32 v10, v10, v234
	v_mul_f32_e32 v11, v11, v234
	v_mul_f32_e32 v12, v12, v234
	v_mul_f32_e32 v13, v13, v234
	v_mul_f32_e32 v14, v14, v234
	v_mul_f32_e32 v15, v15, v234
	v_mul_f32_e32 v16, v16, v234
	v_mul_f32_e32 v17, v17, v234
	v_mul_f32_e32 v18, v18, v234
	v_mul_f32_e32 v19, v19, v234
	v_mul_f32_e32 v20, v20, v234
	v_mul_f32_e32 v21, v21, v234
	v_mul_f32_e32 v22, v22, v234
	v_mul_f32_e32 v23, v23, v234
	v_mul_f32_e32 v24, v24, v234
	v_mul_f32_e32 v25, v25, v234
	v_mul_f32_e32 v26, v26, v234
	v_mul_f32_e32 v27, v27, v234
	v_mul_f32_e32 v28, v28, v234
	v_mul_f32_e32 v29, v29, v234
	v_mul_f32_e32 v30, v30, v234
	v_mul_f32_e32 v31, v31, v234
	v_mul_f32_e32 v32, v32, v235
	v_mul_f32_e32 v33, v33, v235
	v_mul_f32_e32 v34, v34, v235
	v_mul_f32_e32 v35, v35, v235
	v_mul_f32_e32 v36, v36, v235
	v_mul_f32_e32 v37, v37, v235
	v_mul_f32_e32 v38, v38, v235
	v_mul_f32_e32 v39, v39, v235
	v_mul_f32_e32 v40, v40, v235
	v_mul_f32_e32 v41, v41, v235
	v_mul_f32_e32 v42, v42, v235
	v_mul_f32_e32 v43, v43, v235
	v_mul_f32_e32 v44, v44, v235
	v_mul_f32_e32 v45, v45, v235
	v_mul_f32_e32 v46, v46, v235
	v_mul_f32_e32 v47, v47, v235
	v_mul_f32_e32 v48, v48, v235
	v_mul_f32_e32 v49, v49, v235
	v_mul_f32_e32 v50, v50, v235
	v_mul_f32_e32 v51, v51, v235
	v_mul_f32_e32 v52, v52, v235
	v_mul_f32_e32 v53, v53, v235
	v_mul_f32_e32 v54, v54, v235
	v_mul_f32_e32 v55, v55, v235
	v_mul_f32_e32 v56, v56, v235
	v_mul_f32_e32 v57, v57, v235
	v_mul_f32_e32 v58, v58, v235
	v_mul_f32_e32 v59, v59, v235
	v_mul_f32_e32 v60, v60, v235
	v_mul_f32_e32 v61, v61, v235
	v_mul_f32_e32 v62, v62, v235
	v_mul_f32_e32 v63, v63, v235
	v_mul_f32_e32 v64, v64, v236
	v_mul_f32_e32 v65, v65, v236
	v_mul_f32_e32 v66, v66, v236
	v_mul_f32_e32 v67, v67, v236
	v_mul_f32_e32 v68, v68, v236
	v_mul_f32_e32 v69, v69, v236
	v_mul_f32_e32 v70, v70, v236
	v_mul_f32_e32 v71, v71, v236
	v_mul_f32_e32 v72, v72, v236
	v_mul_f32_e32 v73, v73, v236
	v_mul_f32_e32 v74, v74, v236
	v_mul_f32_e32 v75, v75, v236
	v_mul_f32_e32 v76, v76, v236
	v_mul_f32_e32 v77, v77, v236
	v_mul_f32_e32 v78, v78, v236
	v_mul_f32_e32 v79, v79, v236
	v_mul_f32_e32 v80, v80, v236
	v_mul_f32_e32 v81, v81, v236
	v_mul_f32_e32 v82, v82, v236
	v_mul_f32_e32 v83, v83, v236
	v_mul_f32_e32 v84, v84, v236
	v_mul_f32_e32 v85, v85, v236
	v_mul_f32_e32 v86, v86, v236
	v_mul_f32_e32 v87, v87, v236
	v_mul_f32_e32 v88, v88, v236
	v_mul_f32_e32 v89, v89, v236
	v_mul_f32_e32 v90, v90, v236
	v_mul_f32_e32 v91, v91, v236
	v_mul_f32_e32 v92, v92, v236
	v_mul_f32_e32 v93, v93, v236
	v_mul_f32_e32 v94, v94, v236
	v_mul_f32_e32 v95, v95, v236
	v_mul_f32_e32 v96, v96, v237
	v_mul_f32_e32 v97, v97, v237
	v_mul_f32_e32 v98, v98, v237
	v_mul_f32_e32 v99, v99, v237
	v_mul_f32_e32 v100, v100, v237
	v_mul_f32_e32 v101, v101, v237
	v_mul_f32_e32 v102, v102, v237
	v_mul_f32_e32 v103, v103, v237
	v_mul_f32_e32 v104, v104, v237
	v_mul_f32_e32 v105, v105, v237
	v_mul_f32_e32 v106, v106, v237
	v_mul_f32_e32 v107, v107, v237
	v_mul_f32_e32 v108, v108, v237
	v_mul_f32_e32 v109, v109, v237
	v_mul_f32_e32 v110, v110, v237
	v_mul_f32_e32 v111, v111, v237
	v_mul_f32_e32 v112, v112, v237
	v_mul_f32_e32 v113, v113, v237
	v_mul_f32_e32 v114, v114, v237
	v_mul_f32_e32 v115, v115, v237
	v_mul_f32_e32 v116, v116, v237
	v_mul_f32_e32 v117, v117, v237
	v_mul_f32_e32 v118, v118, v237
	v_mul_f32_e32 v119, v119, v237
	v_mul_f32_e32 v120, v120, v237
	v_mul_f32_e32 v121, v121, v237
	v_mul_f32_e32 v122, v122, v237
	v_mul_f32_e32 v123, v123, v237
	v_mul_f32_e32 v124, v124, v237
	v_mul_f32_e32 v125, v125, v237
	v_mul_f32_e32 v126, v126, v237
	v_mul_f32_e32 v127, v127, v237
	s_cmp_eq_u32 s30, 0
	s_cbranch_scc1 .Lgm_norelu
; template <int EPI> ...
;     ...
;     if (EPI == EPI_SCALE || EPI == EPI_PLAIN || EPI == EPI_FF1) {
; #pragma unroll
;       for (int i = 0; i < 16; i++) {
;         const int rl = rbase + (i & 3) + 8 * (i >> 2);
;         const int row = m0 + rl;
;         float v0 = acc0[i], v1 = acc1[i];
;         if (EPI != EPI_PLAIN) { float rs = sRs[rl]; v0 *= rs; v1 *= rs; }
;         if (EPI == EPI_FF1) { v0 = fmaxf(v0, 0.f); v1 = fmaxf(v1, 0.f); v0 *= v0; v1 *= v1; }
;         outb[(size_t)row * ldo + c0] = f2bf(v0);
;         outb[(size_t)row * ldo + c1] = f2bf(v1);
;       }
	v_max_f32_e32 v0, 0, v0
	v_mul_f32_e32 v0, v0, v0
	v_max_f32_e32 v1, 0, v1
	v_mul_f32_e32 v1, v1, v1
	v_max_f32_e32 v2, 0, v2
	v_mul_f32_e32 v2, v2, v2
	v_max_f32_e32 v3, 0, v3
	v_mul_f32_e32 v3, v3, v3
	v_max_f32_e32 v4, 0, v4
	v_mul_f32_e32 v4, v4, v4
	v_max_f32_e32 v5, 0, v5
	v_mul_f32_e32 v5, v5, v5
	v_max_f32_e32 v6, 0, v6
	v_mul_f32_e32 v6, v6, v6
	v_max_f32_e32 v7, 0, v7
	v_mul_f32_e32 v7, v7, v7
	v_max_f32_e32 v8, 0, v8
	v_mul_f32_e32 v8, v8, v8
	v_max_f32_e32 v9, 0, v9
	v_mul_f32_e32 v9, v9, v9
	v_max_f32_e32 v10, 0, v10
	v_mul_f32_e32 v10, v10, v10
	v_max_f32_e32 v11, 0, v11
	v_mul_f32_e32 v11, v11, v11
	v_max_f32_e32 v12, 0, v12
	v_mul_f32_e32 v12, v12, v12
	v_max_f32_e32 v13, 0, v13
	v_mul_f32_e32 v13, v13, v13
	v_max_f32_e32 v14, 0, v14
	v_mul_f32_e32 v14, v14, v14
	v_max_f32_e32 v15, 0, v15
	v_mul_f32_e32 v15, v15, v15
	v_max_f32_e32 v16, 0, v16
	v_mul_f32_e32 v16, v16, v16
	v_max_f32_e32 v17, 0, v17
	v_mul_f32_e32 v17, v17, v17
	v_max_f32_e32 v18, 0, v18
	v_mul_f32_e32 v18, v18, v18
	v_max_f32_e32 v19, 0, v19
	v_mul_f32_e32 v19, v19, v19
	v_max_f32_e32 v20, 0, v20
	v_mul_f32_e32 v20, v20, v20
	v_max_f32_e32 v21, 0, v21
	v_mul_f32_e32 v21, v21, v21
	v_max_f32_e32 v22, 0, v22
	v_mul_f32_e32 v22, v22, v22
	v_max_f32_e32 v23, 0, v23
	v_mul_f32_e32 v23, v23, v23
	v_max_f32_e32 v24, 0, v24
	v_mul_f32_e32 v24, v24, v24
	v_max_f32_e32 v25, 0, v25
	v_mul_f32_e32 v25, v25, v25
	v_max_f32_e32 v26, 0, v26
	v_mul_f32_e32 v26, v26, v26
	v_max_f32_e32 v27, 0, v27
	v_mul_f32_e32 v27, v27, v27
	v_max_f32_e32 v28, 0, v28
	v_mul_f32_e32 v28, v28, v28
	v_max_f32_e32 v29, 0, v29
	v_mul_f32_e32 v29, v29, v29
	v_max_f32_e32 v30, 0, v30
	v_mul_f32_e32 v30, v30, v30
	v_max_f32_e32 v31, 0, v31
	v_mul_f32_e32 v31, v31, v31
	v_max_f32_e32 v32, 0, v32
	v_mul_f32_e32 v32, v32, v32
	v_max_f32_e32 v33, 0, v33
	v_mul_f32_e32 v33, v33, v33
	v_max_f32_e32 v34, 0, v34
	v_mul_f32_e32 v34, v34, v34
	v_max_f32_e32 v35, 0, v35
	v_mul_f32_e32 v35, v35, v35
	v_max_f32_e32 v36, 0, v36
	v_mul_f32_e32 v36, v36, v36
	v_max_f32_e32 v37, 0, v37
	v_mul_f32_e32 v37, v37, v37
	v_max_f32_e32 v38, 0, v38
	v_mul_f32_e32 v38, v38, v38
	v_max_f32_e32 v39, 0, v39
	v_mul_f32_e32 v39, v39, v39
	v_max_f32_e32 v40, 0, v40
	v_mul_f32_e32 v40, v40, v40
	v_max_f32_e32 v41, 0, v41
	v_mul_f32_e32 v41, v41, v41
	v_max_f32_e32 v42, 0, v42
	v_mul_f32_e32 v42, v42, v42
	v_max_f32_e32 v43, 0, v43
	v_mul_f32_e32 v43, v43, v43
	v_max_f32_e32 v44, 0, v44
	v_mul_f32_e32 v44, v44, v44
	v_max_f32_e32 v45, 0, v45
	v_mul_f32_e32 v45, v45, v45
	v_max_f32_e32 v46, 0, v46
	v_mul_f32_e32 v46, v46, v46
	v_max_f32_e32 v47, 0, v47
	v_mul_f32_e32 v47, v47, v47
	v_max_f32_e32 v48, 0, v48
	v_mul_f32_e32 v48, v48, v48
	v_max_f32_e32 v49, 0, v49
	v_mul_f32_e32 v49, v49, v49
	v_max_f32_e32 v50, 0, v50
	v_mul_f32_e32 v50, v50, v50
	v_max_f32_e32 v51, 0, v51
	v_mul_f32_e32 v51, v51, v51
	v_max_f32_e32 v52, 0, v52
	v_mul_f32_e32 v52, v52, v52
	v_max_f32_e32 v53, 0, v53
	v_mul_f32_e32 v53, v53, v53
	v_max_f32_e32 v54, 0, v54
	v_mul_f32_e32 v54, v54, v54
	v_max_f32_e32 v55, 0, v55
	v_mul_f32_e32 v55, v55, v55
	v_max_f32_e32 v56, 0, v56
	v_mul_f32_e32 v56, v56, v56
	v_max_f32_e32 v57, 0, v57
	v_mul_f32_e32 v57, v57, v57
	v_max_f32_e32 v58, 0, v58
	v_mul_f32_e32 v58, v58, v58
	v_max_f32_e32 v59, 0, v59
	v_mul_f32_e32 v59, v59, v59
	v_max_f32_e32 v60, 0, v60
	v_mul_f32_e32 v60, v60, v60
	v_max_f32_e32 v61, 0, v61
	v_mul_f32_e32 v61, v61, v61
	v_max_f32_e32 v62, 0, v62
	v_mul_f32_e32 v62, v62, v62
	v_max_f32_e32 v63, 0, v63
	v_mul_f32_e32 v63, v63, v63
	v_max_f32_e32 v64, 0, v64
	v_mul_f32_e32 v64, v64, v64
	v_max_f32_e32 v65, 0, v65
; template <int EPI> ...
;     ...
;     if (EPI == EPI_SCALE || EPI == EPI_PLAIN || EPI == EPI_FF1) {
; #pragma unroll
;       for (int i = 0; i < 16; i++) {
;         const int rl = rbase + (i & 3) + 8 * (i >> 2);
;         const int row = m0 + rl;
;         float v0 = acc0[i], v1 = acc1[i];
;         if (EPI != EPI_PLAIN) { float rs = sRs[rl]; v0 *= rs; v1 *= rs; }
;         if (EPI == EPI_FF1) { v0 = fmaxf(v0, 0.f); v1 = fmaxf(v1, 0.f); v0 *= v0; v1 *= v1; }
;         outb[(size_t)row * ldo + c0] = f2bf(v0);
;         outb[(size_t)row * ldo + c1] = f2bf(v1);
;       }
	v_mul_f32_e32 v65, v65, v65
	v_max_f32_e32 v66, 0, v66
	v_mul_f32_e32 v66, v66, v66
	v_max_f32_e32 v67, 0, v67
	v_mul_f32_e32 v67, v67, v67
	v_max_f32_e32 v68, 0, v68
	v_mul_f32_e32 v68, v68, v68
	v_max_f32_e32 v69, 0, v69
	v_mul_f32_e32 v69, v69, v69
	v_max_f32_e32 v70, 0, v70
	v_mul_f32_e32 v70, v70, v70
	v_max_f32_e32 v71, 0, v71
	v_mul_f32_e32 v71, v71, v71
	v_max_f32_e32 v72, 0, v72
	v_mul_f32_e32 v72, v72, v72
	v_max_f32_e32 v73, 0, v73
	v_mul_f32_e32 v73, v73, v73
	v_max_f32_e32 v74, 0, v74
	v_mul_f32_e32 v74, v74, v74
	v_max_f32_e32 v75, 0, v75
	v_mul_f32_e32 v75, v75, v75
	v_max_f32_e32 v76, 0, v76
	v_mul_f32_e32 v76, v76, v76
	v_max_f32_e32 v77, 0, v77
	v_mul_f32_e32 v77, v77, v77
	v_max_f32_e32 v78, 0, v78
	v_mul_f32_e32 v78, v78, v78
	v_max_f32_e32 v79, 0, v79
	v_mul_f32_e32 v79, v79, v79
	v_max_f32_e32 v80, 0, v80
	v_mul_f32_e32 v80, v80, v80
	v_max_f32_e32 v81, 0, v81
	v_mul_f32_e32 v81, v81, v81
	v_max_f32_e32 v82, 0, v82
	v_mul_f32_e32 v82, v82, v82
	v_max_f32_e32 v83, 0, v83
	v_mul_f32_e32 v83, v83, v83
	v_max_f32_e32 v84, 0, v84
	v_mul_f32_e32 v84, v84, v84
	v_max_f32_e32 v85, 0, v85
	v_mul_f32_e32 v85, v85, v85
	v_max_f32_e32 v86, 0, v86
	v_mul_f32_e32 v86, v86, v86
	v_max_f32_e32 v87, 0, v87
	v_mul_f32_e32 v87, v87, v87
	v_max_f32_e32 v88, 0, v88
	v_mul_f32_e32 v88, v88, v88
	v_max_f32_e32 v89, 0, v89
	v_mul_f32_e32 v89, v89, v89
	v_max_f32_e32 v90, 0, v90
	v_mul_f32_e32 v90, v90, v90
	v_max_f32_e32 v91, 0, v91
	v_mul_f32_e32 v91, v91, v91
	v_max_f32_e32 v92, 0, v92
	v_mul_f32_e32 v92, v92, v92
	v_max_f32_e32 v93, 0, v93
	v_mul_f32_e32 v93, v93, v93
	v_max_f32_e32 v94, 0, v94
	v_mul_f32_e32 v94, v94, v94
	v_max_f32_e32 v95, 0, v95
	v_mul_f32_e32 v95, v95, v95
	v_max_f32_e32 v96, 0, v96
	v_mul_f32_e32 v96, v96, v96
	v_max_f32_e32 v97, 0, v97
	v_mul_f32_e32 v97, v97, v97
	v_max_f32_e32 v98, 0, v98
	v_mul_f32_e32 v98, v98, v98
	v_max_f32_e32 v99, 0, v99
	v_mul_f32_e32 v99, v99, v99
	v_max_f32_e32 v100, 0, v100
	v_mul_f32_e32 v100, v100, v100
	v_max_f32_e32 v101, 0, v101
	v_mul_f32_e32 v101, v101, v101
	v_max_f32_e32 v102, 0, v102
	v_mul_f32_e32 v102, v102, v102
	v_max_f32_e32 v103, 0, v103
	v_mul_f32_e32 v103, v103, v103
	v_max_f32_e32 v104, 0, v104
	v_mul_f32_e32 v104, v104, v104
	v_max_f32_e32 v105, 0, v105
	v_mul_f32_e32 v105, v105, v105
	v_max_f32_e32 v106, 0, v106
	v_mul_f32_e32 v106, v106, v106
	v_max_f32_e32 v107, 0, v107
	v_mul_f32_e32 v107, v107, v107
	v_max_f32_e32 v108, 0, v108
	v_mul_f32_e32 v108, v108, v108
	v_max_f32_e32 v109, 0, v109
	v_mul_f32_e32 v109, v109, v109
	v_max_f32_e32 v110, 0, v110
	v_mul_f32_e32 v110, v110, v110
	v_max_f32_e32 v111, 0, v111
	v_mul_f32_e32 v111, v111, v111
	v_max_f32_e32 v112, 0, v112
	v_mul_f32_e32 v112, v112, v112
	v_max_f32_e32 v113, 0, v113
	v_mul_f32_e32 v113, v113, v113
	v_max_f32_e32 v114, 0, v114
	v_mul_f32_e32 v114, v114, v114
	v_max_f32_e32 v115, 0, v115
	v_mul_f32_e32 v115, v115, v115
	v_max_f32_e32 v116, 0, v116
	v_mul_f32_e32 v116, v116, v116
	v_max_f32_e32 v117, 0, v117
	v_mul_f32_e32 v117, v117, v117
	v_max_f32_e32 v118, 0, v118
	v_mul_f32_e32 v118, v118, v118
	v_max_f32_e32 v119, 0, v119
	v_mul_f32_e32 v119, v119, v119
	v_max_f32_e32 v120, 0, v120
	v_mul_f32_e32 v120, v120, v120
	v_max_f32_e32 v121, 0, v121
	v_mul_f32_e32 v121, v121, v121
	v_max_f32_e32 v122, 0, v122
	v_mul_f32_e32 v122, v122, v122
	v_max_f32_e32 v123, 0, v123
	v_mul_f32_e32 v123, v123, v123
	v_max_f32_e32 v124, 0, v124
	v_mul_f32_e32 v124, v124, v124
	v_max_f32_e32 v125, 0, v125
	v_mul_f32_e32 v125, v125, v125
	v_max_f32_e32 v126, 0, v126
	v_mul_f32_e32 v126, v126, v126
	v_max_f32_e32 v127, 0, v127
	v_mul_f32_e32 v127, v127, v127

; template <int EPI>
; __device__ __forceinline__ void gemm_phase(const Params& p, const u16* __restrict__ A, int lda, const u16* __restrict__ BT, int ldb,
;                            int K, int N, u16* __restrict__ outb, int ldo, int resid_in, int boff) {
;     ...
;     const int m0 = mt * 256, n0 = nt * 128;
;     const u16* gA = A + (size_t)(m0 + lrow) * lda + lch * 8 + (size_t)kbeg * 64;
;     const u16* gB = BT + (size_t)(n0 + lrow) * ldb + lch * 8 + (size_t)kbeg * 64;
;     ...
;     float4 pq0 = make_float4(0.f, 0.f, 0.f, 0.f), pq1 = pq0, pq2 = pq0, pq3 = pq0;
;     if (EPI == EPI_SCALE || EPI == EPI_FF1) {
;       const float4* pp = (const float4*)(part + (size_t)(m0 + (tid & 255)) * 16);
;       pq0 = pp[0]; pq1 = pp[1]; pq2 = pp[2]; pq3 = pp[3];
;     }
.Lgm_dec_done_p0:
	s_mov_b32 s11, 1
	s_mov_b32 s18, s9
	s_add_u32 s36, s45, 8
	s_lshl_b32 s36, s6, s36
	s_lshl_b32 s37, s8, 7
	s_add_u32 s36, s36, s37
	s_add_u32 s0, s16, s36
	s_addc_u32 s1, s17, 0
	s_add_u32 s36, s46, 7
	s_lshl_b32 s36, s7, s36
	s_add_u32 s36, s36, s37
	s_add_u32 s2, s20, s36
	s_addc_u32 s3, s21, 0
	s_cmp_ge_u32 s30, 3
	s_cbranch_scc1 .Lgp_su_done_p0
	s_mov_b32 s12, 1
	s_lshl_b32 s36, s6, 8
	v_add_u32_e32 v160, s36, v165
	v_lshlrev_b32_e32 v160, 6, v160

; #define PH(n, sync_) if (plo <= (n) && (n) <= phi) { if ((n) > plo && (sync_)) { if ((n) == 1) { grid.sync(); xb = xcd_barrier_post((unsigned*)(ws + O_XBAR), (volatile LAS unsigned*)&xb_words); } else xcd_barrier(xb); }
; __global__ void __launch_bounds__(512) mega(Params p, int plo, int phi) {
;     ...
;   PH(20, 1) res_fix_phase(p); PHEND
;   PH(21, 1) final_phase(p); PHEND
.LBB0_2232:
	s_cmp_lt_i32 s40, 21
	s_cselect_b64 s[4:5], -1, 0
	s_branch .LBB0_2289

; __device__ __forceinline__ void final_phase(const Params& p) {
;   const float* part = (const float*)(p.ws + O_PART);
;   const float* g = p.in[40];
;   const int lane = threadIdx.x & 63, wave = threadIdx.x >> 6;
;   for (int row = blockIdx.x * 8 + wave; row < MT; row += gridDim.x * 8) {
;     float s = (lane < 16) ? part[(size_t)row * 16 + lane] : 0.f;
;     s = wsum64(s);
;     const float rs = rsqrtf(s * (1.0f / 1024.0f) + 1e-6f);
;     float* xr = p.out + (size_t)row * 1024;
; #pragma unroll
;     for (int i = 0; i < 4; i++) {
;       float4 v = *(float4*)(xr + i * 256 + lane * 4);
;       float4 gg = *(const float4*)(g + i * 256 + lane * 4);
;       v.x *= rs * gg.x; v.y *= rs * gg.y; v.z *= rs * gg.z; v.w *= rs * gg.w;
;       *(float4*)(xr + i * 256 + lane * 4) = v;
;     }
;   }
; }
.LBB0_2340:
	v_lshrrev_b32_e32 v42, 6, v128
	v_and_b32_e32 v43, 63, v128
	v_readlane_b32 s1, v254, 0
	v_readfirstlane_b32 s0, v42
	v_lshlrev_b32_e32 v40, 4, v43
	v_and_b32_e32 v44, 15, v43
	v_lshlrev_b32_e32 v41, 2, v44
	v_cmp_gt_u32_e32 vcc, 16, v43
	s_lshl_b32 s1, s1, 3
	s_add_u32 s2, s1, s0
	s_lshl_b32 s12, s42, 3
	s_add_u32 s96, s96, 0x2e00100
	s_addc_u32 s97, s97, 0
	global_load_dwordx4 v[16:19], v40, s[92:93]
	global_load_dwordx4 v[20:23], v40, s[92:93] offset:1024
	global_load_dwordx4 v[24:27], v40, s[92:93] offset:2048
	global_load_dwordx4 v[28:31], v40, s[92:93] offset:3072
	s_mov_b32 s14, s2
	s_lshl_b32 s4, s2, 12
	s_add_u32 s8, s94, s4
	s_addc_u32 s9, s95, 0
	s_lshl_b32 s4, s2, 6
	s_add_u32 s6, s96, s4
	s_addc_u32 s7, s97, 0
	global_load_dwordx4 v[0:3], v40, s[8:9]
	global_load_dwordx4 v[4:7], v40, s[8:9] offset:1024
	global_load_dwordx4 v[8:11], v40, s[8:9] offset:2048
	global_load_dwordx4 v[12:15], v40, s[8:9] offset:3072
	global_load_dword v32, v41, s[6:7]
	s_add_u32 s2, s2, s12
	s_mov_b32 s15, s2
	s_lshl_b32 s4, s2, 12
	s_add_u32 s10, s94, s4
	s_addc_u32 s11, s95, 0
	s_lshl_b32 s4, s2, 6
	s_add_u32 s6, s96, s4
	s_addc_u32 s7, s97, 0
	global_load_dwordx4 v[48:51], v40, s[10:11]
	global_load_dwordx4 v[52:55], v40, s[10:11] offset:1024
	global_load_dwordx4 v[56:59], v40, s[10:11] offset:2048
	global_load_dwordx4 v[60:63], v40, s[10:11] offset:3072
	global_load_dword v80, v41, s[6:7]
	s_waitcnt vmcnt(5)
	s_cmp_lt_u32 s14, 16384
	s_cbranch_scc1 .Lfin_prompt_f
	v_mul_f32_e32 v42, v0, v0
	v_fmac_f32_e32 v42, v1, v1
	v_fmac_f32_e32 v42, v2, v2
	v_fmac_f32_e32 v42, v3, v3
	v_fmac_f32_e32 v42, v4, v4
	v_fmac_f32_e32 v42, v5, v5
	v_fmac_f32_e32 v42, v6, v6
	v_fmac_f32_e32 v42, v7, v7
	v_fmac_f32_e32 v42, v8, v8
	v_fmac_f32_e32 v42, v9, v9
	v_fmac_f32_e32 v42, v10, v10
	v_fmac_f32_e32 v42, v11, v11
	v_fmac_f32_e32 v42, v12, v12
	v_fmac_f32_e32 v42, v13, v13
	v_fmac_f32_e32 v42, v14, v14
	v_fmac_f32_e32 v42, v15, v15
	s_branch .Lfin_sum_f
.Lfin_prompt_f:
	v_cndmask_b32_e32 v42, 0, v32, vcc
.Lfin_sum_f:
	s_nop 1
	v_add_f32_dpp v42, v42, v42 quad_perm:[1,0,3,2] row_mask:0xf bank_mask:0xf
	s_nop 1
	v_add_f32_dpp v42, v42, v42 quad_perm:[2,3,0,1] row_mask:0xf bank_mask:0xf
	s_nop 1
	v_add_f32_dpp v42, v42, v42 row_half_mirror row_mask:0xf bank_mask:0xf
	s_nop 1
	v_add_f32_dpp v42, v42, v42 row_mirror row_mask:0xf bank_mask:0xf
	v_mov_b32_e32 v43, v42
	s_nop 1
	v_permlane16_swap_b32_e32 v43, v42
	v_add_f32_e32 v42, v42, v43
	v_mov_b32_e32 v43, v42
	s_nop 1
	v_permlane32_swap_b32_e32 v43, v42
	v_add_f32_e32 v42, v42, v43
	v_mov_b32_e32 v43, 0x358637bd
	v_fmamk_f32 v42, v42, 0x3a800000, v43
	v_rsq_f32_e32 v42, v42
	s_nop 0
	v_mul_f32_e32 v44, v42, v16
	v_mul_f32_e32 v0, v0, v44
	v_mul_f32_e32 v45, v42, v17
	v_mul_f32_e32 v1, v1, v45
	v_mul_f32_e32 v46, v42, v18
	v_mul_f32_e32 v2, v2, v46
	v_mul_f32_e32 v47, v42, v19
	v_mul_f32_e32 v3, v3, v47
	v_mul_f32_e32 v44, v42, v20
	v_mul_f32_e32 v4, v4, v44
	v_mul_f32_e32 v45, v42, v21
	v_mul_f32_e32 v5, v5, v45
	v_mul_f32_e32 v46, v42, v22
	v_mul_f32_e32 v6, v6, v46
	v_mul_f32_e32 v47, v42, v23
	v_mul_f32_e32 v7, v7, v47
	v_mul_f32_e32 v44, v42, v24
	v_mul_f32_e32 v8, v8, v44
	v_mul_f32_e32 v45, v42, v25
	v_mul_f32_e32 v9, v9, v45
	v_mul_f32_e32 v46, v42, v26
	v_mul_f32_e32 v10, v10, v46
	v_mul_f32_e32 v47, v42, v27
	v_mul_f32_e32 v11, v11, v47
	v_mul_f32_e32 v44, v42, v28
	v_mul_f32_e32 v12, v12, v44
	v_mul_f32_e32 v45, v42, v29
	v_mul_f32_e32 v13, v13, v45
	v_mul_f32_e32 v46, v42, v30
	v_mul_f32_e32 v14, v14, v46
	v_mul_f32_e32 v47, v42, v31
	v_mul_f32_e32 v15, v15, v47
	global_store_dwordx4 v40, v[0:3], s[8:9]
	global_store_dwordx4 v40, v[4:7], s[8:9] offset:1024
	global_store_dwordx4 v40, v[8:11], s[8:9] offset:2048
	global_store_dwordx4 v40, v[12:15], s[8:9] offset:3072
; __device__ __forceinline__ void final_phase(const Params& p) {
;   const float* part = (const float*)(p.ws + O_PART);
;   const float* g = p.in[40];
;   const int lane = threadIdx.x & 63, wave = threadIdx.x >> 6;
;   for (int row = blockIdx.x * 8 + wave; row < MT; row += gridDim.x * 8) {
;     float s = (lane < 16) ? part[(size_t)row * 16 + lane] : 0.f;
;     s = wsum64(s);
;     const float rs = rsqrtf(s * (1.0f / 1024.0f) + 1e-6f);
;     float* xr = p.out + (size_t)row * 1024;
; #pragma unroll
;     for (int i = 0; i < 4; i++) {
;       float4 v = *(float4*)(xr + i * 256 + lane * 4);
;       float4 gg = *(const float4*)(g + i * 256 + lane * 4);
;       v.x *= rs * gg.x; v.y *= rs * gg.y; v.z *= rs * gg.z; v.w *= rs * gg.w;
;       *(float4*)(xr + i * 256 + lane * 4) = v;
;     }
;   }
; }
.Lfin_loop:
	s_mov_b32 s13, 0
	s_add_u32 s2, s2, s12
	s_cmp_ge_u32 s2, 16896
	s_cbranch_scc1 .Lfin_nomore_a
	s_mov_b32 s14, s2
	s_lshl_b32 s4, s2, 12
	s_add_u32 s8, s94, s4
	s_addc_u32 s9, s95, 0
	s_lshl_b32 s4, s2, 6
	s_add_u32 s6, s96, s4
	s_addc_u32 s7, s97, 0
	global_load_dwordx4 v[0:3], v40, s[8:9]
	global_load_dwordx4 v[4:7], v40, s[8:9] offset:1024
	global_load_dwordx4 v[8:11], v40, s[8:9] offset:2048
	global_load_dwordx4 v[12:15], v40, s[8:9] offset:3072
	global_load_dword v32, v41, s[6:7]
	s_waitcnt vmcnt(9)
	s_branch .Lfin_go_a
.Lfin_nomore_a:
	s_mov_b32 s13, 1
	s_waitcnt vmcnt(0)
.Lfin_go_a:
	s_cmp_lt_u32 s15, 16384
	s_cbranch_scc1 .Lfin_prompt_a
	v_mul_f32_e32 v42, v48, v48
	v_fmac_f32_e32 v42, v49, v49
	v_fmac_f32_e32 v42, v50, v50
	v_fmac_f32_e32 v42, v51, v51
	v_fmac_f32_e32 v42, v52, v52
	v_fmac_f32_e32 v42, v53, v53
	v_fmac_f32_e32 v42, v54, v54
	v_fmac_f32_e32 v42, v55, v55
	v_fmac_f32_e32 v42, v56, v56
	v_fmac_f32_e32 v42, v57, v57
	v_fmac_f32_e32 v42, v58, v58
	v_fmac_f32_e32 v42, v59, v59
	v_fmac_f32_e32 v42, v60, v60
	v_fmac_f32_e32 v42, v61, v61
	v_fmac_f32_e32 v42, v62, v62
	v_fmac_f32_e32 v42, v63, v63
	s_branch .Lfin_sum_a
.Lfin_prompt_a:
	v_cndmask_b32_e32 v42, 0, v80, vcc
.Lfin_sum_a:
	s_nop 1
	v_add_f32_dpp v42, v42, v42 quad_perm:[1,0,3,2] row_mask:0xf bank_mask:0xf
	s_nop 1
	v_add_f32_dpp v42, v42, v42 quad_perm:[2,3,0,1] row_mask:0xf bank_mask:0xf
	s_nop 1
	v_add_f32_dpp v42, v42, v42 row_half_mirror row_mask:0xf bank_mask:0xf
	s_nop 1
	v_add_f32_dpp v42, v42, v42 row_mirror row_mask:0xf bank_mask:0xf
	v_mov_b32_e32 v43, v42
	s_nop 1
	v_permlane16_swap_b32_e32 v43, v42
	v_add_f32_e32 v42, v42, v43
	v_mov_b32_e32 v43, v42
	s_nop 1
	v_permlane32_swap_b32_e32 v43, v42
	v_add_f32_e32 v42, v42, v43
	v_mov_b32_e32 v43, 0x358637bd
	v_fmamk_f32 v42, v42, 0x3a800000, v43
	v_rsq_f32_e32 v42, v42
	s_nop 0
	v_mul_f32_e32 v44, v42, v16
	v_mul_f32_e32 v48, v48, v44
	v_mul_f32_e32 v45, v42, v17
	v_mul_f32_e32 v49, v49, v45
	v_mul_f32_e32 v46, v42, v18
	v_mul_f32_e32 v50, v50, v46
	v_mul_f32_e32 v47, v42, v19
	v_mul_f32_e32 v51, v51, v47
	v_mul_f32_e32 v44, v42, v20
	v_mul_f32_e32 v52, v52, v44
	v_mul_f32_e32 v45, v42, v21
	v_mul_f32_e32 v53, v53, v45
	v_mul_f32_e32 v46, v42, v22
	v_mul_f32_e32 v54, v54, v46
	v_mul_f32_e32 v47, v42, v23
	v_mul_f32_e32 v55, v55, v47
	v_mul_f32_e32 v44, v42, v24
	v_mul_f32_e32 v56, v56, v44
	v_mul_f32_e32 v45, v42, v25
	v_mul_f32_e32 v57, v57, v45
	v_mul_f32_e32 v46, v42, v26
	v_mul_f32_e32 v58, v58, v46
	v_mul_f32_e32 v47, v42, v27
	v_mul_f32_e32 v59, v59, v47
	v_mul_f32_e32 v44, v42, v28
	v_mul_f32_e32 v60, v60, v44
	v_mul_f32_e32 v45, v42, v29
	v_mul_f32_e32 v61, v61, v45
	v_mul_f32_e32 v46, v42, v30
	v_mul_f32_e32 v62, v62, v46
	v_mul_f32_e32 v47, v42, v31
	v_mul_f32_e32 v63, v63, v47
	global_store_dwordx4 v40, v[48:51], s[10:11]
	global_store_dwordx4 v40, v[52:55], s[10:11] offset:1024
	global_store_dwordx4 v40, v[56:59], s[10:11] offset:2048
	global_store_dwordx4 v40, v[60:63], s[10:11] offset:3072
	s_cmp_eq_u32 s13, 1
	s_cbranch_scc1 .Lfin_done
	s_mov_b32 s13, 0
	s_add_u32 s2, s2, s12
	s_cmp_ge_u32 s2, 16896
	s_cbranch_scc1 .Lfin_nomore_b
	s_mov_b32 s15, s2
	s_lshl_b32 s4, s2, 12
	s_add_u32 s10, s94, s4
	s_addc_u32 s11, s95, 0
	s_lshl_b32 s4, s2, 6
	s_add_u32 s6, s96, s4
	s_addc_u32 s7, s97, 0
	global_load_dwordx4 v[48:51], v40, s[10:11]
	global_load_dwordx4 v[52:55], v40, s[10:11] offset:1024
	global_load_dwordx4 v[56:59], v40, s[10:11] offset:2048
	global_load_dwordx4 v[60:63], v40, s[10:11] offset:3072
	global_load_dword v80, v41, s[6:7]
	s_waitcnt vmcnt(9)
	s_branch .Lfin_go_b

; __device__ __forceinline__ void final_phase(const Params& p) {
;   const float* part = (const float*)(p.ws + O_PART);
;   const float* g = p.in[40];
;   const int lane = threadIdx.x & 63, wave = threadIdx.x >> 6;
;   for (int row = blockIdx.x * 8 + wave; row < MT; row += gridDim.x * 8) {
;     float s = (lane < 16) ? part[(size_t)row * 16 + lane] : 0.f;
;     s = wsum64(s);
;     const float rs = rsqrtf(s * (1.0f / 1024.0f) + 1e-6f);
;     float* xr = p.out + (size_t)row * 1024;
; #pragma unroll
;     for (int i = 0; i < 4; i++) {
;       float4 v = *(float4*)(xr + i * 256 + lane * 4);
;       float4 gg = *(const float4*)(g + i * 256 + lane * 4);
;       v.x *= rs * gg.x; v.y *= rs * gg.y; v.z *= rs * gg.z; v.w *= rs * gg.w;
;       *(float4*)(xr + i * 256 + lane * 4) = v;
;     }
;   }
; }
.Lfin_go_b:
	s_cmp_lt_u32 s14, 16384
	s_cbranch_scc1 .Lfin_prompt_b
	v_mul_f32_e32 v42, v0, v0
	v_fmac_f32_e32 v42, v1, v1
	v_fmac_f32_e32 v42, v2, v2
	v_fmac_f32_e32 v42, v3, v3
	v_fmac_f32_e32 v42, v4, v4
	v_fmac_f32_e32 v42, v5, v5
	v_fmac_f32_e32 v42, v6, v6
	v_fmac_f32_e32 v42, v7, v7
	v_fmac_f32_e32 v42, v8, v8
	v_fmac_f32_e32 v42, v9, v9
	v_fmac_f32_e32 v42, v10, v10
	v_fmac_f32_e32 v42, v11, v11
	v_fmac_f32_e32 v42, v12, v12
	v_fmac_f32_e32 v42, v13, v13
	v_fmac_f32_e32 v42, v14, v14
	v_fmac_f32_e32 v42, v15, v15
	s_branch .Lfin_sum_b

; __device__ __forceinline__ void final_phase(const Params& p) {
;   const float* part = (const float*)(p.ws + O_PART);
;   const float* g = p.in[40];
;   const int lane = threadIdx.x & 63, wave = threadIdx.x >> 6;
;   for (int row = blockIdx.x * 8 + wave; row < MT; row += gridDim.x * 8) {
;     float s = (lane < 16) ? part[(size_t)row * 16 + lane] : 0.f;
;     s = wsum64(s);
;     const float rs = rsqrtf(s * (1.0f / 1024.0f) + 1e-6f);
;     float* xr = p.out + (size_t)row * 1024;
; #pragma unroll
;     for (int i = 0; i < 4; i++) {
;       float4 v = *(float4*)(xr + i * 256 + lane * 4);
;       float4 gg = *(const float4*)(g + i * 256 + lane * 4);
;       v.x *= rs * gg.x; v.y *= rs * gg.y; v.z *= rs * gg.z; v.w *= rs * gg.w;
;       *(float4*)(xr + i * 256 + lane * 4) = v;
;     }
;   }
; }
.Lfin_sum_b:
	s_nop 1
	v_add_f32_dpp v42, v42, v42 quad_perm:[1,0,3,2] row_mask:0xf bank_mask:0xf
	s_nop 1
	v_add_f32_dpp v42, v42, v42 quad_perm:[2,3,0,1] row_mask:0xf bank_mask:0xf
	s_nop 1
	v_add_f32_dpp v42, v42, v42 row_half_mirror row_mask:0xf bank_mask:0xf
	s_nop 1
	v_add_f32_dpp v42, v42, v42 row_mirror row_mask:0xf bank_mask:0xf
	v_mov_b32_e32 v43, v42
	s_nop 1
	v_permlane16_swap_b32_e32 v43, v42
	v_add_f32_e32 v42, v42, v43
	v_mov_b32_e32 v43, v42
	s_nop 1
	v_permlane32_swap_b32_e32 v43, v42
	v_add_f32_e32 v42, v42, v43
	v_mov_b32_e32 v43, 0x358637bd
	v_fmamk_f32 v42, v42, 0x3a800000, v43
	v_rsq_f32_e32 v42, v42
	s_nop 0
	v_mul_f32_e32 v44, v42, v16
	v_mul_f32_e32 v0, v0, v44
	v_mul_f32_e32 v45, v42, v17
	v_mul_f32_e32 v1, v1, v45
	v_mul_f32_e32 v46, v42, v18
	v_mul_f32_e32 v2, v2, v46
	v_mul_f32_e32 v47, v42, v19
	v_mul_f32_e32 v3, v3, v47
	v_mul_f32_e32 v44, v42, v20
	v_mul_f32_e32 v4, v4, v44
	v_mul_f32_e32 v45, v42, v21
	v_mul_f32_e32 v5, v5, v45
	v_mul_f32_e32 v46, v42, v22
	v_mul_f32_e32 v6, v6, v46
	v_mul_f32_e32 v47, v42, v23
	v_mul_f32_e32 v7, v7, v47
	v_mul_f32_e32 v44, v42, v24
	v_mul_f32_e32 v8, v8, v44
	v_mul_f32_e32 v45, v42, v25
	v_mul_f32_e32 v9, v9, v45
	v_mul_f32_e32 v46, v42, v26
	v_mul_f32_e32 v10, v10, v46
	v_mul_f32_e32 v47, v42, v27
	v_mul_f32_e32 v11, v11, v47
	v_mul_f32_e32 v44, v42, v28
	v_mul_f32_e32 v12, v12, v44
	v_mul_f32_e32 v45, v42, v29
	v_mul_f32_e32 v13, v13, v45
	v_mul_f32_e32 v46, v42, v30
	v_mul_f32_e32 v14, v14, v46
	v_mul_f32_e32 v47, v42, v31
	v_mul_f32_e32 v15, v15, v47
	global_store_dwordx4 v40, v[0:3], s[8:9]
	global_store_dwordx4 v40, v[4:7], s[8:9] offset:1024
	global_store_dwordx4 v40, v[8:11], s[8:9] offset:2048
	global_store_dwordx4 v40, v[12:15], s[8:9] offset:3072
	s_cmp_eq_u32 s13, 1
	s_cbranch_scc1 .Lfin_done
	s_branch .Lfin_loop
.Lfin_done:
	s_waitcnt vmcnt(0)
.LBB0_2345:
	s_endpgm
